# v85 plus ph3 load balance: the 198 q-up GEMM tiles go to workgroups 56..253 (unit index (bid+200)&255) instead of 0..197, which also carry three LoRA tiles and the second kv-up tile
# speedup vs baseline: 1.0099x; 1.0099x over previous
;     __device__ __forceinline__ bool next(int i, Unit& u) const {
;         const long L = (long)i * G + c; if (L >= nwg) return false;
;         int wgid = (int)L; { const int q = nwg / NXCD, r = nwg % NXCD, xcd = wgid % NXCD, off = wgid / NXCD; wgid = (xcd < r ? xcd * (q + 1) : r * (q + 1) + (xcd - r) * q) + off; }
;         const int nig = WGM * nN, gid = wgid / nig, fm = gid * WGM, gsz = (nM - fm) < WGM ? (nM - fm) : WGM;
;         u.pm = fm + ((wgid % nig) % gsz); u.pn = (wgid % nig) / gsz; return true;
; __global__ void __launch_bounds__(NTHREADS, 2) fwd_kernel(Args args) {
;     ...
;                 pg8::Gemm g{(const bf16_t*)(ws + WS_QL), (const bf16_t*)(ws + WS_WUQ) + (size_t)l * 1536 * 512, MROWS, 1536, 512, 512, 512};
;                 pg8::StaticOrder S; S.init(MROWS, 1536, F.nb, F.bid);
;                 pg8::EpiBf16<0> E{(bf16_t*)(ws + WS_Q), 1536};
;                 pg8::gemm_phase(F.lds, g, S, E, F.tid);
.LBB0_592:
	v_readlane_b32 s4, v253, 0
	v_readlane_b32 s16, v253, 12
	v_readlane_b32 s17, v253, 13
	v_mbcnt_lo_u32_b32 v129, -1, 0
	v_mbcnt_hi_u32_b32 v129, -1, v129
	v_readlane_b32 s5, v253, 1
	v_readlane_b32 s6, v253, 2
	v_readlane_b32 s7, v253, 3
	v_readlane_b32 s8, v253, 4
	v_readlane_b32 s9, v253, 5
	v_readlane_b32 s10, v253, 6
	v_readlane_b32 s11, v253, 7
	v_readlane_b32 s12, v253, 8
	v_readlane_b32 s13, v253, 9
	v_readlane_b32 s14, v253, 10
	v_readlane_b32 s15, v253, 11
	v_readlane_b32 s18, v253, 14
	v_readlane_b32 s19, v253, 15
	v_lshl_add_u32 v0, s82, 6, v129
	v_writelane_b32 v253, s4, 0
	s_mov_b32 s28, 8
	s_add_i32 s60, s96, 0xc8
	s_and_b32 s60, s60, 0xff
	s_cmpk_gt_i32 s60, 0xc5
	v_writelane_b32 v253, s5, 1
	v_writelane_b32 v253, s6, 2
	v_writelane_b32 v253, s7, 3
	v_writelane_b32 v253, s8, 4
	v_writelane_b32 v253, s9, 5
	v_writelane_b32 v253, s10, 6
	v_writelane_b32 v253, s11, 7
	v_writelane_b32 v253, s12, 8
	v_writelane_b32 v253, s13, 9
	v_writelane_b32 v253, s14, 10
	v_writelane_b32 v253, s15, 11
	v_writelane_b32 v253, s16, 12
	v_writelane_b32 v253, s17, 13
	v_writelane_b32 v253, s18, 14
	v_writelane_b32 v253, s19, 15
	v_readfirstlane_b32 s5, v0
	s_cbranch_scc1 .LBB0_618
	s_ashr_i32 s29, s60, 31
	s_lshr_b32 s0, s29, 29
	s_add_i32 s7, s60, s0
	s_and_b32 s0, s7, -8
	s_sub_i32 s6, s60, s0
	s_cmp_gt_i32 s6, 5
	s_mov_b64 s[0:1], -1
	s_cbranch_scc0 .LBB0_595
	s_mul_i32 s0, s6, 24
	s_or_b32 s4, s0, 6
	s_mov_b64 s[0:1], 0

;     __device__ __forceinline__ bool next(int i, Unit& u) const {
;         const long L = (long)i * G + c; if (L >= nwg) return false;
;         int wgid = (int)L; { const int q = nwg / NXCD, r = nwg % NXCD, xcd = wgid % NXCD, off = wgid / NXCD; wgid = (xcd < r ? xcd * (q + 1) : r * (q + 1) + (xcd - r) * q) + off; }
;         const int nig = WGM * nN, gid = wgid / nig, fm = gid * WGM, gsz = (nM - fm) < WGM ? (nM - fm) : WGM;
;         u.pm = fm + ((wgid % nig) % gsz); u.pn = (wgid % nig) / gsz; return true;
.LBB0_602:
	s_add_i32 s44, s44, 1
	s_mul_i32 s4, s44, s46
	s_mul_hi_u32 s5, s44, s84
	s_add_i32 s5, s5, s4
	s_mul_i32 s4, s44, s84
	s_add_u32 s18, s4, s60
	s_addc_u32 s19, s5, s29
	v_mov_b64_e32 v[148:149], 0xc6
	v_cmp_lt_i64_e64 s[4:5], s[18:19], v[148:149]
	v_mov_b64_e32 v[148:149], 0xc5
	v_cmp_gt_i64_e32 vcc, s[18:19], v[148:149]
	s_cbranch_vccnz .LBB0_608
	s_ashr_i32 s12, s18, 31
	s_lshr_b32 s12, s12, 29
	s_add_i32 s14, s18, s12
	s_and_b32 s12, s14, -8
	s_sub_i32 s15, s18, s12
	s_cmp_gt_i32 s15, 5
	s_mov_b64 s[12:13], -1
	s_cbranch_scc0 .LBB0_605
	s_mul_i32 s12, s15, 24
	s_or_b32 s18, s12, 6
	s_mov_b64 s[12:13], 0
